# filter synthesis first layer: 33 weight loads in flight instead of one round trip each
# speedup vs baseline: 1.0677x; 1.0677x over previous
; DI float sin_f(float x) { float s_, c_; sincos_f(x, s_, c_); return s_; }
; DI void filter_item(const PX& p, int it, float* sm) {
;     ...
;   const float fr = p.in[14][l * 64 + i];
;   {
;     float s = p.in[10][l * 64 + i];
;     const float* w1 = p.in[9] + (size_t)l * 33 * 64;
; #pragma unroll 11
;     for (int f = 0; f < 33; f++) s += feats[lg * 40 + f] * w1[f * 64 + i];
;     h1[lg * 64 + i] = sin_f(fr * s);
;   }
;   __syncthreads();
.LBB0_875:
	v_lshl_add_u64 v[12:13], v[4:5], 0, s[4:5]
	s_mov_b64 s[4:5], 0xb00
	v_lshl_add_u64 v[96:97], v[12:13], 0, s[4:5]
	s_mov_b64 s[4:5], 0x1600
	v_lshl_add_u64 v[98:99], v[12:13], 0, s[4:5]
	global_load_dword v142, v[12:13], off
	global_load_dword v143, v[12:13], off offset:256
	global_load_dword v144, v[12:13], off offset:512
	global_load_dword v145, v[12:13], off offset:768
	global_load_dword v146, v[12:13], off offset:1024
	global_load_dword v147, v[12:13], off offset:1280
	global_load_dword v148, v[12:13], off offset:1536
	global_load_dword v149, v[12:13], off offset:1792
	global_load_dword v150, v[12:13], off offset:2048
	global_load_dword v151, v[12:13], off offset:2304
	global_load_dword v152, v[12:13], off offset:2560
	global_load_dword v153, v[96:97], off
	global_load_dword v154, v[96:97], off offset:256
	global_load_dword v155, v[96:97], off offset:512
	global_load_dword v156, v[96:97], off offset:768
	global_load_dword v157, v[96:97], off offset:1024
	global_load_dword v158, v[96:97], off offset:1280
	global_load_dword v159, v[96:97], off offset:1536
	global_load_dword v160, v[96:97], off offset:1792
	global_load_dword v161, v[96:97], off offset:2048
	global_load_dword v162, v[96:97], off offset:2304
	global_load_dword v163, v[96:97], off offset:2560
	global_load_dword v164, v[98:99], off
	global_load_dword v165, v[98:99], off offset:256
	global_load_dword v166, v[98:99], off offset:512
	global_load_dword v167, v[98:99], off offset:768
	global_load_dword v168, v[98:99], off offset:1024
	global_load_dword v169, v[98:99], off offset:1280
	global_load_dword v170, v[98:99], off offset:1536
	global_load_dword v171, v[98:99], off offset:1792
	global_load_dword v172, v[98:99], off offset:2048
	global_load_dword v173, v[98:99], off offset:2304
	global_load_dword v174, v[98:99], off offset:2560
	ds_read2_b32 v[216:217], v7 offset0:0 offset1:1
	ds_read2_b32 v[218:219], v7 offset0:2 offset1:3
	ds_read2_b32 v[220:221], v7 offset0:4 offset1:5
	ds_read2_b32 v[222:223], v7 offset0:6 offset1:7
	ds_read2_b32 v[224:225], v7 offset0:8 offset1:9
	ds_read2_b32 v[226:227], v7 offset0:10 offset1:11
	ds_read2_b32 v[228:229], v7 offset0:12 offset1:13
	ds_read2_b32 v[230:231], v7 offset0:14 offset1:15
	ds_read2_b32 v[232:233], v7 offset0:16 offset1:17
	ds_read2_b32 v[234:235], v7 offset0:18 offset1:19
	ds_read2_b32 v[236:237], v7 offset0:20 offset1:21
	ds_read2_b32 v[238:239], v7 offset0:22 offset1:23
	ds_read2_b32 v[240:241], v7 offset0:24 offset1:25
	ds_read2_b32 v[242:243], v7 offset0:26 offset1:27
	ds_read2_b32 v[244:245], v7 offset0:28 offset1:29
	ds_read2_b32 v[246:247], v7 offset0:30 offset1:31
	ds_read_b32 v248, v7 offset:128
	s_waitcnt vmcnt(32) lgkmcnt(15)
	v_fmac_f32_e32 v8, v216, v142
	s_waitcnt vmcnt(31) lgkmcnt(15)
	v_fmac_f32_e32 v8, v217, v143
	s_waitcnt vmcnt(30) lgkmcnt(14)
	v_fmac_f32_e32 v8, v218, v144
	s_waitcnt vmcnt(29) lgkmcnt(14)
	v_fmac_f32_e32 v8, v219, v145
	s_waitcnt vmcnt(28) lgkmcnt(13)
	v_fmac_f32_e32 v8, v220, v146
	s_waitcnt vmcnt(27) lgkmcnt(13)
	v_fmac_f32_e32 v8, v221, v147
	s_waitcnt vmcnt(26) lgkmcnt(12)
	v_fmac_f32_e32 v8, v222, v148
	s_waitcnt vmcnt(25) lgkmcnt(12)
	v_fmac_f32_e32 v8, v223, v149
	s_waitcnt vmcnt(24) lgkmcnt(11)
	v_fmac_f32_e32 v8, v224, v150
	s_waitcnt vmcnt(23) lgkmcnt(11)
	v_fmac_f32_e32 v8, v225, v151
	s_waitcnt vmcnt(22) lgkmcnt(10)
	v_fmac_f32_e32 v8, v226, v152
	s_waitcnt vmcnt(21) lgkmcnt(10)
	v_fmac_f32_e32 v8, v227, v153
	s_waitcnt vmcnt(20) lgkmcnt(9)
	v_fmac_f32_e32 v8, v228, v154
	s_waitcnt vmcnt(19) lgkmcnt(9)
	v_fmac_f32_e32 v8, v229, v155
	s_waitcnt vmcnt(18) lgkmcnt(8)
	v_fmac_f32_e32 v8, v230, v156
	s_waitcnt vmcnt(17) lgkmcnt(8)
	v_fmac_f32_e32 v8, v231, v157
	s_waitcnt vmcnt(16) lgkmcnt(7)
	v_fmac_f32_e32 v8, v232, v158
	s_waitcnt vmcnt(15) lgkmcnt(7)
	v_fmac_f32_e32 v8, v233, v159
	s_waitcnt vmcnt(14) lgkmcnt(6)
	v_fmac_f32_e32 v8, v234, v160
	s_waitcnt vmcnt(13) lgkmcnt(6)
	v_fmac_f32_e32 v8, v235, v161
	s_waitcnt vmcnt(12) lgkmcnt(5)
	v_fmac_f32_e32 v8, v236, v162
	s_waitcnt vmcnt(11) lgkmcnt(5)
	v_fmac_f32_e32 v8, v237, v163
	s_waitcnt vmcnt(10) lgkmcnt(4)
	v_fmac_f32_e32 v8, v238, v164
	s_waitcnt vmcnt(9) lgkmcnt(4)
	v_fmac_f32_e32 v8, v239, v165
	s_waitcnt vmcnt(8) lgkmcnt(3)
	v_fmac_f32_e32 v8, v240, v166
	s_waitcnt vmcnt(7) lgkmcnt(3)
	v_fmac_f32_e32 v8, v241, v167
	s_waitcnt vmcnt(6) lgkmcnt(2)
	v_fmac_f32_e32 v8, v242, v168
	s_waitcnt vmcnt(5) lgkmcnt(2)
	v_fmac_f32_e32 v8, v243, v169
	s_waitcnt vmcnt(4) lgkmcnt(1)
	v_fmac_f32_e32 v8, v244, v170
	s_waitcnt vmcnt(3) lgkmcnt(1)
	v_fmac_f32_e32 v8, v245, v171
	s_waitcnt vmcnt(2) lgkmcnt(0)
	v_fmac_f32_e32 v8, v246, v172
	s_waitcnt vmcnt(1) lgkmcnt(0)
	v_fmac_f32_e32 v8, v247, v173
	s_waitcnt vmcnt(0) lgkmcnt(0)
	v_fmac_f32_e32 v8, v248, v174
	v_mul_f32_e32 v7, v6, v8
	v_mul_f32_e32 v4, 0x3f22f983, v7
	v_rndne_f32_e32 v4, v4
	v_fmac_f32_e32 v7, 0xbfc90000, v4
	v_fmac_f32_e32 v7, 0xb9fda000, v4
	v_fmac_f32_e32 v7, 0xb3a22169, v4
	v_cvt_i32_f32_e32 v8, v4
	v_mul_f32_e32 v4, v7, v7
	v_mov_b32_e32 v9, 0x3c08839e
	v_fmamk_f32 v9, v4, 0xb94ca1f9, v9
	v_mul_f32_e32 v5, v7, v4
	v_fmaak_f32 v9, v4, v9, 0xbe2aaaa3
	v_fmac_f32_e32 v7, v5, v9
	v_mov_b32_e32 v5, 0xbab6061a
	v_fmamk_f32 v187, v4, 0x37ccf5ce, v5
	v_mul_f32_e32 v9, v4, v4
	v_pk_mul_f32 v[4:5], v[4:5], v[186:187] op_sel_hi:[0,1]
	v_add_f32_e32 v5, 0x3d2aaaa5, v5
	v_sub_f32_e32 v4, 1.0, v4
	v_fmac_f32_e32 v4, v9, v5
	v_and_b32_e32 v5, 1, v8
	v_cmp_eq_u32_e32 vcc, 0, v5
	v_and_b32_e32 v5, 2, v8
	v_readlane_b32 s8, v252, 19
	v_cndmask_b32_e32 v4, v4, v7, vcc
	v_cmp_eq_u32_e32 vcc, 0, v5
	v_readlane_b32 s16, v252, 27
	v_readlane_b32 s17, v252, 28
	v_cndmask_b32_e64 v5, -v4, v4, vcc
	v_lshlrev_b32_e32 v4, 2, v54
	v_lshl_add_u64 v[8:9], v[0:1], 2, s[16:17]
	ds_write_b32 v4, v5 offset:1280
	s_waitcnt lgkmcnt(0)
	s_barrier
	global_load_dword v0, v[8:9], off
	v_readlane_b32 s4, v253, 31
	v_readlane_b32 s5, v253, 32
	v_readlane_b32 s14, v252, 25
	s_lshl_b64 s[4:5], s[4:5], 14
	v_readlane_b32 s15, v252, 26
	s_add_u32 s4, s14, s4
	v_and_b32_e32 v5, 0xffffff00, v4
	s_addc_u32 s5, s15, s5
	v_add_u32_e32 v5, 0x500, v5
	v_lshl_add_u64 v[2:3], s[4:5], 0, v[2:3]
	s_mov_b64 s[4:5], 0
	v_readlane_b32 s9, v252, 20
	v_readlane_b32 s10, v252, 21
	v_readlane_b32 s11, v252, 22
	v_readlane_b32 s12, v252, 23
	v_readlane_b32 s13, v252, 24
	v_readlane_b32 s18, v252, 29
	v_readlane_b32 s19, v252, 30
	v_readlane_b32 s20, v252, 31
	v_readlane_b32 s21, v252, 32
	v_readlane_b32 s22, v252, 33
	v_readlane_b32 s23, v252, 34
